# grid barriers: acquire invalidate issued right after arrival; non-leaders poll the cross-XCD generation directly
# speedup vs baseline: 1.0194x; 1.0194x over previous
.LBB0_71:
	s_or_b64 exec, exec, s[6:7]
	v_cvt_f32_u32_e32 v4, v2
	s_waitcnt vmcnt(0)
	v_readfirstlane_b32 s0, v3
	v_sub_u32_e32 v3, 0, v2
	v_rcp_iflag_f32_e32 v4, v4
	v_add_u32_e32 v5, s0, v1
	v_mul_f32_e32 v4, 0x4f7ffffe, v4
	v_cvt_u32_f32_e32 v4, v4
	v_mul_lo_u32 v1, v3, v4
	v_mul_hi_u32 v1, v4, v1
	v_add_u32_e32 v1, v4, v1
	v_mul_hi_u32 v1, v5, v1
	v_mul_lo_u32 v3, v1, v2
	v_sub_u32_e32 v3, v5, v3
	v_add_u32_e32 v4, 1, v1
	v_sub_u32_e32 v6, v3, v2
	v_cmp_ge_u32_e32 vcc, v3, v2
	s_nop 1
	v_cndmask_b32_e32 v1, v1, v4, vcc
	v_cndmask_b32_e32 v3, v3, v6, vcc
	v_add_u32_e32 v4, 1, v1
	v_cmp_ge_u32_e32 vcc, v3, v2
	v_add_u32_e32 v3, 1, v5
	s_nop 0
	v_cndmask_b32_e32 v1, v1, v4, vcc
	v_mul_lo_u32 v4, v2, v1
	v_add_u32_e32 v2, v4, v2
	v_cmp_ne_u32_e32 vcc, v3, v2
	s_and_saveexec_b64 s[0:1], vcc
	s_xor_b64 s[6:7], exec, s[0:1]
	s_cbranch_execz .LBB0_85
	v_readlane_b32 s0, v239, 47
	s_waitcnt lgkmcnt(0)
	v_mov_b32_e32 v0, 0
	v_readlane_b32 s1, v239, 48
	s_nop 4
	buffer_inv sc1
	global_load_dword v2, v0, s[0:1] sc1
	s_waitcnt vmcnt(0)
	v_cmp_eq_u32_e32 vcc, v2, v1
	s_and_saveexec_b64 s[8:9], vcc
	s_cbranch_execz .LBB0_84
	s_mov_b32 s0, 1
	s_mov_b64 s[10:11], 0
	s_branch .LBB0_75

.LBB0_77:
	v_readlane_b32 s12, v239, 47
	v_readlane_b32 s13, v239, 48
	s_add_i32 s0, s0, 1
	s_mov_b64 s[30:31], -1
	s_nop 2
	global_load_dword v2, v0, s[12:13] sc1
	s_waitcnt vmcnt(0)
	v_cmp_ne_u32_e32 vcc, v2, v1
	s_orn2_b64 s[28:29], vcc, exec
	s_branch .LBB0_74

.LBB0_84:
	s_or_b64 exec, exec, s[8:9]
	s_waitcnt vmcnt(0)
	s_waitcnt vmcnt(0)
.LBB0_85:
	s_andn2_saveexec_b64 s[0:1], s[6:7]
	s_cbranch_execz .LBB0_105
	s_mov_b64 s[6:7], exec
	buffer_wbl2 sc1
	s_waitcnt lgkmcnt(0)
	s_waitcnt vmcnt(0)
	buffer_inv sc1
	v_mbcnt_lo_u32_b32 v1, s6, 0
	v_mbcnt_hi_u32_b32 v1, s7, v1
	v_cmp_eq_u32_e32 vcc, 0, v1
	s_and_saveexec_b64 s[8:9], vcc
	s_cbranch_execz .LBB0_88
	s_bcnt1_i32_b64 s0, s[6:7]
	v_mov_b32_e32 v3, s0
	v_readlane_b32 s0, v239, 45
	v_mov_b32_e32 v2, 0
	v_readlane_b32 s1, v239, 46
	s_nop 4
	global_atomic_add v2, v2, v3, s[0:1] sc0

.LBB0_102:
	s_or_b64 exec, exec, s[6:7]
	s_mov_b64 s[6:7], exec
	v_mbcnt_lo_u32_b32 v0, s6, 0
	v_mbcnt_hi_u32_b32 v0, s7, v0
	v_cmp_eq_u32_e32 vcc, 0, v0
	s_waitcnt vmcnt(0)
	s_and_saveexec_b64 s[8:9], vcc
	s_cbranch_execz .LBB0_104
	s_bcnt1_i32_b64 s0, s[6:7]
	v_mov_b32_e32 v1, s0
	v_readlane_b32 s0, v239, 43
	v_mov_b32_e32 v0, 0
	v_readlane_b32 s1, v239, 44
	s_nop 4
	global_atomic_add v0, v1, s[0:1]

.LBB0_303:
	s_or_b64 exec, exec, s[10:11]
	v_cvt_f32_u32_e32 v4, v2
	s_waitcnt vmcnt(0)
	v_readfirstlane_b32 s0, v3
	v_sub_u32_e32 v3, 0, v2
	v_rcp_iflag_f32_e32 v4, v4
	v_add_u32_e32 v5, s0, v1
	v_mul_f32_e32 v4, 0x4f7ffffe, v4
	v_cvt_u32_f32_e32 v4, v4
	v_mul_lo_u32 v1, v3, v4
	v_mul_hi_u32 v1, v4, v1
	v_add_u32_e32 v1, v4, v1
	v_mul_hi_u32 v1, v5, v1
	v_mul_lo_u32 v3, v1, v2
	v_sub_u32_e32 v3, v5, v3
	v_add_u32_e32 v4, 1, v1
	v_cmp_ge_u32_e32 vcc, v3, v2
	s_nop 1
	v_cndmask_b32_e32 v1, v1, v4, vcc
	v_sub_u32_e32 v4, v3, v2
	v_cndmask_b32_e32 v3, v3, v4, vcc
	v_add_u32_e32 v4, 1, v1
	v_cmp_ge_u32_e32 vcc, v3, v2
	v_add_u32_e32 v3, 1, v5
	s_nop 0
	v_cndmask_b32_e32 v1, v1, v4, vcc
	v_mul_lo_u32 v4, v2, v1
	v_add_u32_e32 v2, v4, v2
	v_cmp_ne_u32_e32 vcc, v3, v2
	s_and_saveexec_b64 s[0:1], vcc
	s_xor_b64 s[10:11], exec, s[0:1]
	s_cbranch_execz .LBB0_317
	v_readlane_b32 s0, v239, 47
	s_waitcnt lgkmcnt(0)
	v_mov_b32_e32 v0, 0
	v_readlane_b32 s1, v239, 48
	s_nop 4
	buffer_inv sc1
	global_load_dword v2, v0, s[0:1] sc1
	s_waitcnt vmcnt(0)
	v_cmp_eq_u32_e32 vcc, v2, v1
	s_and_saveexec_b64 s[18:19], vcc
	s_cbranch_execz .LBB0_316
	s_mov_b32 s0, 1
	s_mov_b64 s[30:31], 0
	s_branch .LBB0_307

.LBB0_309:
	v_readlane_b32 s12, v239, 47
	v_readlane_b32 s13, v239, 48
	s_add_i32 s0, s0, 1
	s_mov_b64 s[38:39], -1
	s_nop 2
	global_load_dword v2, v0, s[12:13] sc1
	s_waitcnt vmcnt(0)
	v_cmp_ne_u32_e32 vcc, v2, v1
	s_orn2_b64 s[36:37], vcc, exec
	s_branch .LBB0_306

.LBB0_316:
	s_or_b64 exec, exec, s[18:19]
	s_waitcnt vmcnt(0)
	s_waitcnt vmcnt(0)
.LBB0_317:
	s_andn2_saveexec_b64 s[0:1], s[10:11]
	s_cbranch_execz .LBB0_337
	s_mov_b64 s[10:11], exec
	buffer_wbl2 sc1
	s_waitcnt lgkmcnt(0)
	s_waitcnt vmcnt(0)
	buffer_inv sc1
	v_mbcnt_lo_u32_b32 v1, s10, 0
	v_mbcnt_hi_u32_b32 v1, s11, v1
	v_cmp_eq_u32_e32 vcc, 0, v1
	s_and_saveexec_b64 s[18:19], vcc
	s_cbranch_execz .LBB0_320
	s_bcnt1_i32_b64 s0, s[10:11]
	v_mov_b32_e32 v3, s0
	v_readlane_b32 s0, v239, 45
	v_mov_b32_e32 v2, 0
	v_readlane_b32 s1, v239, 46
	s_nop 4
	global_atomic_add v2, v2, v3, s[0:1] sc0

.LBB0_334:
	s_or_b64 exec, exec, s[10:11]
	s_mov_b64 s[10:11], exec
	v_mbcnt_lo_u32_b32 v0, s10, 0
	v_mbcnt_hi_u32_b32 v0, s11, v0
	v_cmp_eq_u32_e32 vcc, 0, v0
	s_waitcnt vmcnt(0)
	s_and_saveexec_b64 s[18:19], vcc
	s_cbranch_execz .LBB0_336
	s_bcnt1_i32_b64 s0, s[10:11]
	v_mov_b32_e32 v1, s0
	v_readlane_b32 s0, v239, 43
	v_mov_b32_e32 v0, 0
	v_readlane_b32 s1, v239, 44
	s_nop 4
	global_atomic_add v0, v1, s[0:1]

.LBB0_590:
	s_or_b64 exec, exec, s[0:1]
	v_cvt_f32_u32_e32 v4, v2
	s_waitcnt vmcnt(0)
	v_readfirstlane_b32 s0, v3
	v_sub_u32_e32 v3, 0, v2
	v_rcp_iflag_f32_e32 v4, v4
	v_add_u32_e32 v5, s0, v1
	v_mul_f32_e32 v4, 0x4f7ffffe, v4
	v_cvt_u32_f32_e32 v4, v4
	v_mul_lo_u32 v1, v3, v4
	v_mul_hi_u32 v1, v4, v1
	v_add_u32_e32 v1, v4, v1
	v_mul_hi_u32 v1, v5, v1
	v_mul_lo_u32 v3, v1, v2
	v_sub_u32_e32 v3, v5, v3
	v_add_u32_e32 v4, 1, v1
	v_cmp_ge_u32_e32 vcc, v3, v2
	s_nop 1
	v_cndmask_b32_e32 v1, v1, v4, vcc
	v_sub_u32_e32 v4, v3, v2
	v_cndmask_b32_e32 v3, v3, v4, vcc
	v_add_u32_e32 v4, 1, v1
	v_cmp_ge_u32_e32 vcc, v3, v2
	v_add_u32_e32 v3, 1, v5
	s_nop 0
	v_cndmask_b32_e32 v1, v1, v4, vcc
	v_mul_lo_u32 v4, v2, v1
	v_add_u32_e32 v2, v4, v2
	v_cmp_ne_u32_e32 vcc, v3, v2
	s_and_saveexec_b64 s[0:1], vcc
	s_xor_b64 s[0:1], exec, s[0:1]
	s_cbranch_execz .LBB0_604
	v_readlane_b32 s6, v239, 47
	s_waitcnt lgkmcnt(0)
	v_mov_b32_e32 v0, 0
	v_readlane_b32 s7, v239, 48
	s_nop 4
	buffer_inv sc1
	global_load_dword v2, v0, s[6:7] sc1
	s_waitcnt vmcnt(0)
	v_cmp_eq_u32_e32 vcc, v2, v1
	s_and_saveexec_b64 s[6:7], vcc
	s_cbranch_execz .LBB0_603
	s_mov_b32 s18, 1
	s_mov_b64 s[8:9], 0
	s_branch .LBB0_594

.LBB0_596:
	v_readlane_b32 s12, v239, 47
	v_readlane_b32 s13, v239, 48
	s_add_i32 s18, s18, 1
	s_mov_b64 s[14:15], -1
	s_nop 2
	global_load_dword v2, v0, s[12:13] sc1
	s_waitcnt vmcnt(0)
	v_cmp_ne_u32_e32 vcc, v2, v1
	s_orn2_b64 s[12:13], vcc, exec
	s_branch .LBB0_593

.LBB0_603:
	s_or_b64 exec, exec, s[6:7]
	s_waitcnt vmcnt(0)
	s_waitcnt vmcnt(0)
.LBB0_604:
	s_andn2_saveexec_b64 s[0:1], s[0:1]
	s_cbranch_execz .LBB0_624
	s_mov_b64 s[0:1], exec
	buffer_wbl2 sc1
	s_waitcnt lgkmcnt(0)
	s_waitcnt vmcnt(0)
	buffer_inv sc1
	v_mbcnt_lo_u32_b32 v1, s0, 0
	v_mbcnt_hi_u32_b32 v1, s1, v1
	v_cmp_eq_u32_e32 vcc, 0, v1
	s_and_saveexec_b64 s[6:7], vcc
	s_cbranch_execz .LBB0_607
	s_bcnt1_i32_b64 s0, s[0:1]
	v_mov_b32_e32 v3, s0
	v_readlane_b32 s0, v239, 45
	v_mov_b32_e32 v2, 0
	v_readlane_b32 s1, v239, 46
	s_nop 4
	global_atomic_add v2, v2, v3, s[0:1] sc0

.LBB0_621:
	s_or_b64 exec, exec, s[0:1]
	s_mov_b64 s[0:1], exec
	v_mbcnt_lo_u32_b32 v0, s0, 0
	v_mbcnt_hi_u32_b32 v0, s1, v0
	v_cmp_eq_u32_e32 vcc, 0, v0
	s_waitcnt vmcnt(0)
	s_and_saveexec_b64 s[6:7], vcc
	s_cbranch_execz .LBB0_623
	s_bcnt1_i32_b64 s0, s[0:1]
	v_mov_b32_e32 v1, s0
	v_readlane_b32 s0, v239, 43
	v_mov_b32_e32 v0, 0
	v_readlane_b32 s1, v239, 44
	s_nop 4
	global_atomic_add v0, v1, s[0:1]
